# v26 + attention: QK^T fragment double-buffer with counted lgkmcnt waits in both MFMA phases; softmax phases: K/V prefetch via SGPR-base addressing (no 64-bit VALU adds), redundant self-max ops dropped
# speedup vs baseline: 1.0071x; 1.0011x over previous
; template <int KB>
; __device__ __forceinline__ void qkt(f32x16& p0, f32x16& p1, const char* K_lds, int r32, int hi, const bf16x8* qr, const float* bl) {
; #pragma unroll
;     for (int g = 0; g < 4; ++g) { const f32x4 a = *(const f32x4*)(bl + 8 * g), b = *(const f32x4*)(bl + 32 + 8 * g);
;         p0[4 * g + 0] = a[0]; p0[4 * g + 1] = a[1]; p0[4 * g + 2] = a[2]; p0[4 * g + 3] = a[3];
;         p1[4 * g + 0] = b[0]; p1[4 * g + 1] = b[1]; p1[4 * g + 2] = b[2]; p1[4 * g + 3] = b[3]; }
;     const char* kb[4];
; #pragma unroll
;     for (int dd = 0; dd < 4; ++dd) kb[dd] = K_lds + KB * SHM_K + KSWZ(r32, (dd * 16 + hi * 8) * 2);
; #pragma unroll
;     for (int d0 = 0; d0 < 8; ++d0) { const char* a = kb[d0 & 3] + (d0 >> 2) * 128;
;         bf16x8 b0 = *reinterpret_cast<const bf16x8*>(a);
;         bf16x8 b1 = *reinterpret_cast<const bf16x8*>(a + 32 * 256);
;         p0 = __builtin_amdgcn_mfma_f32_32x32x16_bf16(b0, qr[d0], p0, 0, 0, 0);
;         p1 = __builtin_amdgcn_mfma_f32_32x32x16_bf16(b1, qr[d0], p1, 0, 0, 0); }
; }
; template <int VB>
; __device__ __forceinline__ void pv_tile(f32x16* o, int vb0, bf16x8 pa0, bf16x8 pa1, bf16x8 pa2, bf16x8 pa3) {
;     ...
;     PV_D0(0); PV_D0(1); PV_D0(2); PV_D0(3);
;     ...
; }
.LBB0_313:
	ds_read_b128 v[84:87], v170
	ds_read_b128 v[88:91], v170 offset:32
	ds_read_b128 v[68:71], v170 offset:128
	ds_read_b128 v[72:75], v170 offset:160
	ds_read_b128 v[92:95], v170 offset:64
	ds_read_b128 v[76:79], v170 offset:192
	ds_read_b128 v[96:99], v170 offset:96
	ds_read_b128 v[80:83], v170 offset:224
	ds_read_b128 v[164:167], v229
	ds_read_b128 v[172:175], v229 offset:8192
	ds_read_b128 v[176:179], v230
	ds_read_b128 v[180:183], v230 offset:8192
	v_lshl_add_u32 v2, s5, 14, v216
	s_waitcnt lgkmcnt(3)
	v_mfma_f32_32x32x16_bf16 v[84:99], v[164:167], v[108:111], v[84:99]
	s_waitcnt lgkmcnt(2)
	v_mfma_f32_32x32x16_bf16 v[68:83], v[172:175], v[108:111], v[68:83]
	ds_read_b128 v[164:167], v231
	ds_read_b128 v[172:175], v231 offset:8192
	s_waitcnt lgkmcnt(3)
	v_mfma_f32_32x32x16_bf16 v[84:99], v[176:179], v[112:115], v[84:99]
	s_waitcnt lgkmcnt(2)
	v_mfma_f32_32x32x16_bf16 v[68:83], v[180:183], v[112:115], v[68:83]
	ds_read_b128 v[176:179], v232
	ds_read_b128 v[180:183], v232 offset:8192
	s_waitcnt lgkmcnt(3)
	v_mfma_f32_32x32x16_bf16 v[84:99], v[164:167], v[116:119], v[84:99]
	s_waitcnt lgkmcnt(2)
	v_mfma_f32_32x32x16_bf16 v[68:83], v[172:175], v[116:119], v[68:83]
	ds_read_b128 v[164:167], v229 offset:128
	ds_read_b128 v[172:175], v229 offset:8320
	s_waitcnt lgkmcnt(3)
	v_mfma_f32_32x32x16_bf16 v[84:99], v[176:179], v[120:123], v[84:99]
	s_waitcnt lgkmcnt(2)
	v_mfma_f32_32x32x16_bf16 v[68:83], v[180:183], v[120:123], v[68:83]
	ds_read_b128 v[176:179], v230 offset:128
	ds_read_b128 v[180:183], v230 offset:8320
	s_waitcnt lgkmcnt(3)
	v_mfma_f32_32x32x16_bf16 v[84:99], v[164:167], v[124:127], v[84:99]
	s_waitcnt lgkmcnt(2)
	v_mfma_f32_32x32x16_bf16 v[68:83], v[172:175], v[124:127], v[68:83]
	ds_read_b128 v[164:167], v231 offset:128
	ds_read_b128 v[172:175], v231 offset:8320
	s_waitcnt lgkmcnt(3)
	v_mfma_f32_32x32x16_bf16 v[84:99], v[176:179], v[128:131], v[84:99]
	s_waitcnt lgkmcnt(2)
	v_mfma_f32_32x32x16_bf16 v[68:83], v[180:183], v[128:131], v[68:83]
	ds_read_b128 v[176:179], v232 offset:128
	ds_read_b128 v[180:183], v232 offset:8320
	s_waitcnt lgkmcnt(3)
	v_mfma_f32_32x32x16_bf16 v[84:99], v[164:167], v[132:135], v[84:99]
	s_waitcnt lgkmcnt(2)
	v_mfma_f32_32x32x16_bf16 v[68:83], v[172:175], v[132:135], v[68:83]
	ds_read_b64_tr_b16 v[164:165], v2 offset:0
	ds_read_b64_tr_b16 v[166:167], v2 offset:0x800
	ds_read_b64_tr_b16 v[172:173], v2 offset:0x1000
	ds_read_b64_tr_b16 v[174:175], v2 offset:0x1800
	s_waitcnt lgkmcnt(5)
	v_mfma_f32_32x32x16_bf16 v[84:99], v[176:179], v[140:143], v[84:99]
	s_waitcnt lgkmcnt(4)
	v_mfma_f32_32x32x16_bf16 v[68:83], v[180:183], v[140:143], v[68:83]
	ds_read_b64_tr_b16 v[176:177], v2 offset:0x2000
	ds_read_b64_tr_b16 v[178:179], v2 offset:0x2800
	ds_read_b64_tr_b16 v[180:181], v2 offset:0x3000
	ds_read_b64_tr_b16 v[182:183], v2 offset:0x3800
	s_waitcnt lgkmcnt(6)
	v_mfma_f32_32x32x16_bf16 v[52:67], v[148:151], v[164:167], v[52:67]
	ds_read_b64_tr_b16 v[164:165], v2 offset:0x200
	ds_read_b64_tr_b16 v[166:167], v2 offset:0xa00
	s_waitcnt lgkmcnt(6)
	v_mfma_f32_32x32x16_bf16 v[52:67], v[152:155], v[172:175], v[52:67]
	ds_read_b64_tr_b16 v[172:173], v2 offset:0x1200
	ds_read_b64_tr_b16 v[174:175], v2 offset:0x1a00
	s_waitcnt lgkmcnt(6)
	v_mfma_f32_32x32x16_bf16 v[52:67], v[156:159], v[176:179], v[52:67]
	ds_read_b64_tr_b16 v[176:177], v2 offset:0x2200
	ds_read_b64_tr_b16 v[178:179], v2 offset:0x2a00
	s_waitcnt lgkmcnt(6)
	v_mfma_f32_32x32x16_bf16 v[52:67], v[160:163], v[180:183], v[52:67]
	ds_read_b64_tr_b16 v[180:181], v2 offset:0x3200
	ds_read_b64_tr_b16 v[182:183], v2 offset:0x3a00
	s_waitcnt lgkmcnt(6)
	v_mfma_f32_32x32x16_bf16 v[36:51], v[148:151], v[164:167], v[36:51]
	ds_read_b64_tr_b16 v[164:165], v2 offset:0x400
	ds_read_b64_tr_b16 v[166:167], v2 offset:0xc00
	s_waitcnt lgkmcnt(6)
	v_mfma_f32_32x32x16_bf16 v[36:51], v[152:155], v[172:175], v[36:51]
	ds_read_b64_tr_b16 v[172:173], v2 offset:0x1400
	ds_read_b64_tr_b16 v[174:175], v2 offset:0x1c00
	s_waitcnt lgkmcnt(6)
	v_mfma_f32_32x32x16_bf16 v[36:51], v[156:159], v[176:179], v[36:51]
	ds_read_b64_tr_b16 v[176:177], v2 offset:0x2400
	ds_read_b64_tr_b16 v[178:179], v2 offset:0x2c00
	s_waitcnt lgkmcnt(6)
	v_mfma_f32_32x32x16_bf16 v[36:51], v[160:163], v[180:183], v[36:51]
	ds_read_b64_tr_b16 v[180:181], v2 offset:0x3400
	ds_read_b64_tr_b16 v[182:183], v2 offset:0x3c00
	s_waitcnt lgkmcnt(6)
	v_mfma_f32_32x32x16_bf16 v[20:35], v[148:151], v[164:167], v[20:35]
	ds_read_b64_tr_b16 v[164:165], v2 offset:0x600
	ds_read_b64_tr_b16 v[166:167], v2 offset:0xe00
	s_waitcnt lgkmcnt(6)
	v_mfma_f32_32x32x16_bf16 v[20:35], v[152:155], v[172:175], v[20:35]
	ds_read_b64_tr_b16 v[172:173], v2 offset:0x1600
	ds_read_b64_tr_b16 v[174:175], v2 offset:0x1e00
	s_waitcnt lgkmcnt(6)
	v_mfma_f32_32x32x16_bf16 v[20:35], v[156:159], v[176:179], v[20:35]
	ds_read_b64_tr_b16 v[176:177], v2 offset:0x2600
	ds_read_b64_tr_b16 v[178:179], v2 offset:0x2e00
	s_waitcnt lgkmcnt(6)
	v_mfma_f32_32x32x16_bf16 v[20:35], v[160:163], v[180:183], v[20:35]
	ds_read_b64_tr_b16 v[180:181], v2 offset:0x3600
	ds_read_b64_tr_b16 v[182:183], v2 offset:0x3e00
	s_waitcnt lgkmcnt(6)
	v_mfma_f32_32x32x16_bf16 v[4:19], v[148:151], v[164:167], v[4:19]
	s_lshl_b32 s1, s0, 14
	s_waitcnt vmcnt(0)
	s_add_i32 s1, s1, 0
	v_add_u32_e32 v2, s1, v214
	s_waitcnt vmcnt(1)
	ds_write_b128 v228, v[136:139] offset:49152
	s_waitcnt vmcnt(0)
	ds_write_b128 v228, v[144:147] offset:57344
	ds_write_b128 v2, v[100:103]
	v_add_u32_e32 v2, s1, v215
	s_waitcnt lgkmcnt(7)
	v_mfma_f32_32x32x16_bf16 v[4:19], v[152:155], v[172:175], v[4:19]
	ds_write_b128 v2, v[104:107]
	s_waitcnt lgkmcnt(6)
	v_mfma_f32_32x32x16_bf16 v[4:19], v[156:159], v[176:179], v[4:19]
	s_waitcnt lgkmcnt(4)
	v_mfma_f32_32x32x16_bf16 v[4:19], v[160:163], v[180:183], v[4:19]
	s_waitcnt lgkmcnt(0)
	s_barrier
	s_add_i32 s4, s3, 2
	s_cmp_le_u32 s4, s2
	s_cselect_b64 s[36:37], -1, 0
	s_cmp_gt_u32 s4, s2
	s_cbranch_scc1 .LBB0_315
	s_add_u32 s98, s20, 0xc000
	s_addc_u32 s99, s21, 0
	s_add_u32 s100, s20, 0xe000
	s_addc_u32 s101, s21, 0
	global_load_dwordx4 v[100:103], v196, s[98:99]
	global_load_dwordx4 v[104:107], v196, s[100:101]
	s_add_u32 s98, s18, 0xc000
	s_addc_u32 s99, s19, 0
	s_add_u32 s100, s18, 0xe000
	s_addc_u32 s101, s19, 0
	global_load_dwordx4 v[136:139], v196, s[98:99]
	global_load_dwordx4 v[144:147], v196, s[100:101]

; __device__ __forceinline__ void partialSM(f32x16& p0, f32x16& p1, float& m_reg, float& mn, float& alpha) {
;     float pmax = p0[0];
; #pragma unroll
;     for (int r = 1; r < 16; ++r) pmax = fmaxf(pmax, p0[r]);
; #pragma unroll
;     for (int r = 0; r < 16; ++r) pmax = fmaxf(pmax, p1[r]);
;     { auto rr = __builtin_amdgcn_permlane32_swap(__float_as_uint(pmax), __float_as_uint(pmax), false, false);
;       pmax = fmaxf(__uint_as_float(rr[0]), __uint_as_float(rr[1])); }
;     constexpr float C2 = 1.4426950408889634f * SCALE;
;     if (__builtin_expect(__all((pmax - m_reg) * SCALE <= THR), 1)) { mn = m_reg; alpha = 1.f; }
;     else { mn = fmaxf(m_reg, pmax); alpha = __builtin_amdgcn_exp2f((m_reg - mn) * C2); m_reg = mn; }
;     const float mnL = -mn * C2;
; #pragma unroll
;     for (int r = 0; r < 16; ++r) p0[r] = fmaf(p0[r], C2, mnL);
; #pragma unroll
;     for (int r = 0; r < 16; ++r) p1[r] = fmaf(p1[r], C2, mnL);
; #pragma unroll
;     for (int r = 0; r < 16; ++r) p0[r] = __builtin_amdgcn_exp2f(p0[r]);
; }
; __device__ __forceinline__ void finishSM(f32x16& p0, f32x16& p1, float alpha, float& l_reg, bf16x8& pa0, bf16x8& pa1, bf16x8& pa2, bf16x8& pa3) {
; #pragma unroll
;     for (int r = 0; r < 16; ++r) p1[r] = __builtin_amdgcn_exp2f(p1[r]);
;     float ps = 0;
; #pragma unroll
;     for (int r = 0; r < 16; ++r) ps += p0[r];
; #pragma unroll
;     for (int r = 0; r < 16; ++r) ps += p1[r];
;     { auto rr = __builtin_amdgcn_permlane32_swap(__float_as_uint(ps), __float_as_uint(ps), false, false);
;       ps = __uint_as_float(rr[0]) + __uint_as_float(rr[1]); }
;     l_reg = l_reg * alpha + ps;
;     ...
;     PK4(p0, 0, pa0); PK4(p0, 8, pa1); PK4(p1, 0, pa2); PK4(p1, 8, pa3);
;     ...
; }
.LBB0_317:
	v_max_f32_e32 v2, v84, v85
	v_max3_f32 v2, v2, v86, v87
	v_max3_f32 v2, v2, v88, v89
	v_max3_f32 v2, v2, v90, v91
	v_max3_f32 v2, v2, v92, v93
	v_max3_f32 v2, v2, v94, v95
	v_max3_f32 v2, v2, v96, v97
	v_max3_f32 v2, v2, v98, v99
	v_max3_f32 v2, v2, v68, v69
	v_max3_f32 v2, v2, v70, v71
	v_max3_f32 v2, v2, v72, v73
	v_max3_f32 v2, v2, v74, v75
	v_max3_f32 v2, v2, v76, v77
	v_max3_f32 v2, v2, v78, v79
	v_max3_f32 v2, v2, v80, v81
	v_max3_f32 v2, v2, v82, v83
	v_mov_b32_e32 v148, v2
	s_nop 1
	v_permlane32_swap_b32_e32 v2, v148
	v_max_f32_e32 v2, v2, v148
	v_sub_f32_e32 v148, v2, v236
	v_mul_f32_e32 v148, 0x3db504f3, v148
	v_cmp_ge_f32_e32 vcc, s15, v148
	v_max_f32_e32 v148, v236, v2
	v_sub_f32_e32 v2, v236, v148
	v_mul_f32_e32 v2, 0x3e0293ee, v2
	v_exp_f32_e32 v2, v2
	s_cmp_eq_u64 vcc, exec
	s_cselect_b64 s[38:39], -1, 0
	v_cndmask_b32_e64 v2, v2, 1.0, s[38:39]
	v_cmp_gt_f32_e32 vcc, 1.0, v2
	s_cbranch_vccz .LBB0_321
	s_and_saveexec_b64 s[40:41], s[16:17]
	ds_write_b32 v234, v2 offset:128
	s_or_b64 exec, exec, s[40:41]
	s_waitcnt lgkmcnt(0)
	ds_read_b128 v[150:153], v205 offset:224
	ds_read_b128 v[154:157], v205 offset:192
	ds_read_b128 v[158:161], v205 offset:160
	ds_read_b128 v[172:175], v205 offset:128
	s_waitcnt lgkmcnt(3)
	v_pk_mul_f32 v[66:67], v[66:67], v[152:153]
	s_waitcnt lgkmcnt(2)
	v_pk_mul_f32 v[62:63], v[62:63], v[156:157]
	s_waitcnt lgkmcnt(1)
	v_pk_mul_f32 v[58:59], v[58:59], v[160:161]
	s_waitcnt lgkmcnt(0)
	v_pk_mul_f32 v[54:55], v[54:55], v[174:175]
	v_pk_mul_f32 v[64:65], v[64:65], v[150:151]
	v_pk_mul_f32 v[60:61], v[60:61], v[154:155]
	v_pk_mul_f32 v[56:57], v[56:57], v[158:159]
	v_pk_mul_f32 v[52:53], v[52:53], v[172:173]
	v_pk_mul_f32 v[50:51], v[50:51], v[152:153]
	v_pk_mul_f32 v[46:47], v[46:47], v[156:157]
	v_pk_mul_f32 v[42:43], v[42:43], v[160:161]
	v_pk_mul_f32 v[38:39], v[38:39], v[174:175]
	v_pk_mul_f32 v[48:49], v[48:49], v[150:151]
	v_pk_mul_f32 v[44:45], v[44:45], v[154:155]
	v_pk_mul_f32 v[40:41], v[40:41], v[158:159]
	v_pk_mul_f32 v[36:37], v[36:37], v[172:173]
	v_pk_mul_f32 v[34:35], v[34:35], v[152:153]
	v_pk_mul_f32 v[30:31], v[30:31], v[156:157]
	v_pk_mul_f32 v[26:27], v[26:27], v[160:161]
	v_pk_mul_f32 v[22:23], v[22:23], v[174:175]
	v_pk_mul_f32 v[32:33], v[32:33], v[150:151]
	v_pk_mul_f32 v[28:29], v[28:29], v[154:155]
	v_pk_mul_f32 v[24:25], v[24:25], v[158:159]
	v_pk_mul_f32 v[20:21], v[20:21], v[172:173]
	v_pk_mul_f32 v[18:19], v[18:19], v[152:153]
	v_pk_mul_f32 v[14:15], v[14:15], v[156:157]
	v_pk_mul_f32 v[10:11], v[10:11], v[160:161]
	v_pk_mul_f32 v[6:7], v[6:7], v[174:175]
	v_pk_mul_f32 v[16:17], v[16:17], v[150:151]
	v_pk_mul_f32 v[12:13], v[12:13], v[154:155]
	v_pk_mul_f32 v[8:9], v[8:9], v[158:159]
	v_pk_mul_f32 v[4:5], v[4:5], v[172:173]
.LBB0_321:
	v_cndmask_b32_e64 v171, v148, v236, s[38:39]
	v_mul_f32_e32 v148, 0xbe0293ee, v171
	v_fmamk_f32 v84, v84, 0x3e0293ee, v148
	v_fmamk_f32 v85, v85, 0x3e0293ee, v148
	v_fmamk_f32 v86, v86, 0x3e0293ee, v148
	v_fmamk_f32 v87, v87, 0x3e0293ee, v148
	v_fmamk_f32 v88, v88, 0x3e0293ee, v148
	v_fmamk_f32 v89, v89, 0x3e0293ee, v148
	v_fmamk_f32 v90, v90, 0x3e0293ee, v148
	v_fmamk_f32 v91, v91, 0x3e0293ee, v148
	v_fmamk_f32 v92, v92, 0x3e0293ee, v148
	v_fmamk_f32 v93, v93, 0x3e0293ee, v148
	v_fmamk_f32 v94, v94, 0x3e0293ee, v148
	v_fmamk_f32 v95, v95, 0x3e0293ee, v148
	v_fmamk_f32 v96, v96, 0x3e0293ee, v148
	v_fmamk_f32 v97, v97, 0x3e0293ee, v148
	v_fmamk_f32 v98, v98, 0x3e0293ee, v148
	v_fmamk_f32 v99, v99, 0x3e0293ee, v148
	v_fmamk_f32 v68, v68, 0x3e0293ee, v148
	v_fmamk_f32 v69, v69, 0x3e0293ee, v148
	v_fmamk_f32 v70, v70, 0x3e0293ee, v148
	v_fmamk_f32 v71, v71, 0x3e0293ee, v148
	v_fmamk_f32 v72, v72, 0x3e0293ee, v148
	v_fmamk_f32 v73, v73, 0x3e0293ee, v148
	v_fmamk_f32 v74, v74, 0x3e0293ee, v148
	v_fmamk_f32 v75, v75, 0x3e0293ee, v148
	v_fmamk_f32 v76, v76, 0x3e0293ee, v148
	v_fmamk_f32 v77, v77, 0x3e0293ee, v148
	v_fmamk_f32 v78, v78, 0x3e0293ee, v148
	v_fmamk_f32 v79, v79, 0x3e0293ee, v148
	v_fmamk_f32 v80, v80, 0x3e0293ee, v148
	v_fmamk_f32 v81, v81, 0x3e0293ee, v148
	v_fmamk_f32 v82, v82, 0x3e0293ee, v148
	v_fmac_f32_e32 v148, 0x3e0293ee, v83
	v_exp_f32_e32 v83, v84
	v_exp_f32_e32 v84, v85
	v_exp_f32_e32 v85, v86
	v_exp_f32_e32 v86, v87
	v_exp_f32_e32 v87, v88
	v_exp_f32_e32 v88, v89
	v_exp_f32_e32 v89, v90
	v_exp_f32_e32 v90, v91
	v_exp_f32_e32 v91, v92
	v_exp_f32_e32 v92, v93
	v_exp_f32_e32 v93, v94
	v_exp_f32_e32 v94, v95
	v_exp_f32_e32 v95, v96
	v_exp_f32_e32 v96, v97
	v_exp_f32_e32 v97, v98
	v_exp_f32_e32 v98, v99
	v_exp_f32_e32 v99, v148
	v_add_f32_e32 v148, 0, v83
	v_add_f32_e32 v148, v84, v148
	v_add_f32_e32 v148, v85, v148
	v_add_f32_e32 v148, v86, v148
	v_add_f32_e32 v148, v87, v148
	v_add_f32_e32 v148, v88, v148
	v_add_f32_e32 v148, v89, v148
	v_add_f32_e32 v148, v90, v148
	v_add_f32_e32 v148, v91, v148
	v_add_f32_e32 v148, v92, v148
	v_add_f32_e32 v148, v93, v148
	v_add_f32_e32 v148, v94, v148
	v_exp_f32_e32 v68, v68
	v_add_f32_e32 v148, v95, v148
	v_exp_f32_e32 v69, v69
	v_add_f32_e32 v148, v96, v148
	v_exp_f32_e32 v70, v70
	v_add_f32_e32 v148, v97, v148
	v_exp_f32_e32 v71, v71
	v_add_f32_e32 v148, v98, v148
	v_exp_f32_e32 v72, v72
	v_add_f32_e32 v148, v68, v148
	v_exp_f32_e32 v73, v73
	v_add_f32_e32 v148, v69, v148
	v_exp_f32_e32 v74, v74
	v_add_f32_e32 v148, v70, v148
	v_exp_f32_e32 v75, v75
	v_add_f32_e32 v148, v71, v148
	v_exp_f32_e32 v76, v76
	v_add_f32_e32 v148, v72, v148
	v_exp_f32_e32 v77, v77
	v_add_f32_e32 v148, v73, v148
	v_exp_f32_e32 v78, v78
	v_add_f32_e32 v148, v74, v148
	v_exp_f32_e32 v79, v79
	v_add_f32_e32 v148, v75, v148
	v_exp_f32_e32 v80, v80
	v_add_f32_e32 v148, v76, v148
	v_exp_f32_e32 v81, v81
	v_add_f32_e32 v148, v77, v148
	v_exp_f32_e32 v82, v82
	v_add_f32_e32 v148, v78, v148
	v_add_f32_e32 v148, v79, v148
	v_add_f32_e32 v148, v80, v148
	v_add_f32_e32 v148, v81, v148
	v_add_f32_e32 v148, v82, v148
	v_add_f32_e32 v172, v99, v148
	v_mov_b32_e32 v173, v172
	s_nop 1
	v_permlane32_swap_b32_e32 v172, v173
	v_cvt_pk_bf16_f32 v148, v83, v84
	v_cvt_pk_bf16_f32 v149, v85, v86
	v_cvt_pk_bf16_f32 v150, v87, v88
	v_cvt_pk_bf16_f32 v151, v89, v90
	v_cvt_pk_bf16_f32 v152, v91, v92
	v_cvt_pk_bf16_f32 v153, v93, v94
	v_cvt_pk_bf16_f32 v154, v95, v96
	v_cvt_pk_bf16_f32 v155, v97, v98
	v_cvt_pk_bf16_f32 v156, v68, v69
	v_cvt_pk_bf16_f32 v157, v70, v71
	v_cvt_pk_bf16_f32 v158, v72, v73
	v_cvt_pk_bf16_f32 v159, v74, v75
	v_cvt_pk_bf16_f32 v160, v76, v77
	v_cvt_pk_bf16_f32 v161, v78, v79
	v_cvt_pk_bf16_f32 v162, v80, v81
	v_cvt_pk_bf16_f32 v163, v82, v99
	s_nop 0
	v_permlane32_swap_b32_e32 v148, v150
	v_permlane32_swap_b32_e32 v149, v151
	v_permlane32_swap_b32_e32 v152, v154
	v_permlane32_swap_b32_e32 v153, v155
	v_permlane32_swap_b32_e32 v156, v158
	v_permlane32_swap_b32_e32 v157, v159
	v_permlane32_swap_b32_e32 v160, v162
	v_permlane32_swap_b32_e32 v161, v163
	s_add_i32 s1, s5, 1
	s_cmp_lg_u32 s5, 2
	s_waitcnt lgkmcnt(0)
	s_barrier
; template <int KB>
; __device__ __forceinline__ void qkt(f32x16& p0, f32x16& p1, const char* K_lds, int r32, int hi, const bf16x8* qr, const float* bl) {
; #pragma unroll
;     for (int g = 0; g < 4; ++g) { const f32x4 a = *(const f32x4*)(bl + 8 * g), b = *(const f32x4*)(bl + 32 + 8 * g);
;         p0[4 * g + 0] = a[0]; p0[4 * g + 1] = a[1]; p0[4 * g + 2] = a[2]; p0[4 * g + 3] = a[3];
;         p1[4 * g + 0] = b[0]; p1[4 * g + 1] = b[1]; p1[4 * g + 2] = b[2]; p1[4 * g + 3] = b[3]; }
;     const char* kb[4];
; #pragma unroll
;     for (int dd = 0; dd < 4; ++dd) kb[dd] = K_lds + KB * SHM_K + KSWZ(r32, (dd * 16 + hi * 8) * 2);
; #pragma unroll
;     for (int d0 = 0; d0 < 8; ++d0) { const char* a = kb[d0 & 3] + (d0 >> 2) * 128;
;         bf16x8 b0 = *reinterpret_cast<const bf16x8*>(a);
;         bf16x8 b1 = *reinterpret_cast<const bf16x8*>(a + 32 * 256);
;         p0 = __builtin_amdgcn_mfma_f32_32x32x16_bf16(b0, qr[d0], p0, 0, 0, 0);
;         p1 = __builtin_amdgcn_mfma_f32_32x32x16_bf16(b1, qr[d0], p1, 0, 0, 0); }
; }
; template <int VB>
; __device__ __forceinline__ void pv_tile(f32x16* o, int vb0, bf16x8 pa0, bf16x8 pa1, bf16x8 pa2, bf16x8 pa3) {
;     ...
;     PV_D0(0); PV_D0(1); PV_D0(2); PV_D0(3);
;     ...
; }
	s_cselect_b32 s1, s1, 0
	s_add_i32 s5, s0, 1
	s_cmp_lg_u32 s0, 2
	s_cselect_b32 s0, s5, 0
	ds_read_b128 v[84:87], v170 offset:256
	ds_read_b128 v[88:91], v170 offset:288
	ds_read_b128 v[68:71], v170 offset:384
	ds_read_b128 v[72:75], v170 offset:416
	ds_read_b128 v[92:95], v170 offset:320
	ds_read_b128 v[76:79], v170 offset:448
	ds_read_b128 v[96:99], v170 offset:352
	ds_read_b128 v[80:83], v170 offset:480
	ds_read_b128 v[174:177], v222 offset:49152
	ds_read_b128 v[178:181], v222 offset:57344
	ds_read_b128 v[182:185], v223 offset:49152
	ds_read_b128 v[186:189], v223 offset:57344
	v_lshl_add_u32 v190, s1, 14, v216
	s_waitcnt lgkmcnt(3)
	v_mfma_f32_32x32x16_bf16 v[84:99], v[174:177], v[108:111], v[84:99]
	s_waitcnt lgkmcnt(2)
	v_mfma_f32_32x32x16_bf16 v[68:83], v[178:181], v[108:111], v[68:83]
	ds_read_b128 v[174:177], v224 offset:49152
	ds_read_b128 v[178:181], v224 offset:57344
	s_waitcnt lgkmcnt(3)
	v_mfma_f32_32x32x16_bf16 v[84:99], v[182:185], v[112:115], v[84:99]
	s_waitcnt lgkmcnt(2)
	v_mfma_f32_32x32x16_bf16 v[68:83], v[186:189], v[112:115], v[68:83]
	ds_read_b128 v[182:185], v225 offset:49152
	ds_read_b128 v[186:189], v225 offset:57344
	s_waitcnt lgkmcnt(3)
	v_mfma_f32_32x32x16_bf16 v[84:99], v[174:177], v[116:119], v[84:99]
	s_waitcnt lgkmcnt(2)
	v_mfma_f32_32x32x16_bf16 v[68:83], v[178:181], v[116:119], v[68:83]
	ds_read_b128 v[174:177], v222 offset:49280
	ds_read_b128 v[178:181], v222 offset:57472
	s_waitcnt lgkmcnt(3)
	v_mfma_f32_32x32x16_bf16 v[84:99], v[182:185], v[120:123], v[84:99]
	s_waitcnt lgkmcnt(2)
	v_mfma_f32_32x32x16_bf16 v[68:83], v[186:189], v[120:123], v[68:83]
	ds_read_b128 v[182:185], v223 offset:49280
	ds_read_b128 v[186:189], v223 offset:57472
	s_waitcnt lgkmcnt(3)
	v_mfma_f32_32x32x16_bf16 v[84:99], v[174:177], v[124:127], v[84:99]
	s_waitcnt lgkmcnt(2)
	v_mfma_f32_32x32x16_bf16 v[68:83], v[178:181], v[124:127], v[68:83]
	ds_read_b128 v[174:177], v224 offset:49280
	ds_read_b128 v[178:181], v224 offset:57472
	s_waitcnt lgkmcnt(3)
	v_mfma_f32_32x32x16_bf16 v[84:99], v[182:185], v[128:131], v[84:99]
	s_waitcnt lgkmcnt(2)
	v_mfma_f32_32x32x16_bf16 v[68:83], v[186:189], v[128:131], v[68:83]
	ds_read_b128 v[182:185], v225 offset:49280
	ds_read_b128 v[186:189], v225 offset:57472
	s_waitcnt lgkmcnt(3)
	v_mfma_f32_32x32x16_bf16 v[84:99], v[174:177], v[132:135], v[84:99]
	s_waitcnt lgkmcnt(2)
	v_mfma_f32_32x32x16_bf16 v[68:83], v[178:181], v[132:135], v[68:83]
	ds_read_b64_tr_b16 v[174:175], v190 offset:0
	ds_read_b64_tr_b16 v[176:177], v190 offset:0x800
	ds_read_b64_tr_b16 v[178:179], v190 offset:0x1000
	ds_read_b64_tr_b16 v[180:181], v190 offset:0x1800
	s_waitcnt lgkmcnt(5)
	v_mfma_f32_32x32x16_bf16 v[84:99], v[182:185], v[140:143], v[84:99]
	s_waitcnt lgkmcnt(4)
	v_mfma_f32_32x32x16_bf16 v[68:83], v[186:189], v[140:143], v[68:83]
	ds_read_b64_tr_b16 v[182:183], v190 offset:0x2000
	ds_read_b64_tr_b16 v[184:185], v190 offset:0x2800
	ds_read_b64_tr_b16 v[186:187], v190 offset:0x3000
	ds_read_b64_tr_b16 v[188:189], v190 offset:0x3800
	s_waitcnt lgkmcnt(6)
	v_mfma_f32_32x32x16_bf16 v[52:67], v[148:151], v[174:177], v[52:67]
	ds_read_b64_tr_b16 v[174:175], v190 offset:0x200
	ds_read_b64_tr_b16 v[176:177], v190 offset:0xa00
	s_waitcnt lgkmcnt(6)
	v_mfma_f32_32x32x16_bf16 v[52:67], v[152:155], v[178:181], v[52:67]
	ds_read_b64_tr_b16 v[178:179], v190 offset:0x1200
	ds_read_b64_tr_b16 v[180:181], v190 offset:0x1a00
	s_waitcnt lgkmcnt(6)
	v_mfma_f32_32x32x16_bf16 v[52:67], v[156:159], v[182:185], v[52:67]
	ds_read_b64_tr_b16 v[182:183], v190 offset:0x2200
	ds_read_b64_tr_b16 v[184:185], v190 offset:0x2a00
	s_waitcnt lgkmcnt(6)
	v_mfma_f32_32x32x16_bf16 v[52:67], v[160:163], v[186:189], v[52:67]
	ds_read_b64_tr_b16 v[186:187], v190 offset:0x3200
	ds_read_b64_tr_b16 v[188:189], v190 offset:0x3a00
	s_waitcnt lgkmcnt(6)
	v_mfma_f32_32x32x16_bf16 v[36:51], v[148:151], v[174:177], v[36:51]
	ds_read_b64_tr_b16 v[174:175], v190 offset:0x400
	ds_read_b64_tr_b16 v[176:177], v190 offset:0xc00
	s_waitcnt lgkmcnt(6)
	v_mfma_f32_32x32x16_bf16 v[36:51], v[152:155], v[178:181], v[36:51]
	ds_read_b64_tr_b16 v[178:179], v190 offset:0x1400
	ds_read_b64_tr_b16 v[180:181], v190 offset:0x1c00
	s_waitcnt lgkmcnt(6)
	v_mfma_f32_32x32x16_bf16 v[36:51], v[156:159], v[182:185], v[36:51]
	ds_read_b64_tr_b16 v[182:183], v190 offset:0x2400
	ds_read_b64_tr_b16 v[184:185], v190 offset:0x2c00
	s_waitcnt lgkmcnt(6)
	v_mfma_f32_32x32x16_bf16 v[36:51], v[160:163], v[186:189], v[36:51]
	ds_read_b64_tr_b16 v[186:187], v190 offset:0x3400
	ds_read_b64_tr_b16 v[188:189], v190 offset:0x3c00
	s_waitcnt lgkmcnt(6)
	v_mfma_f32_32x32x16_bf16 v[20:35], v[148:151], v[174:177], v[20:35]
	ds_read_b64_tr_b16 v[174:175], v190 offset:0x600
	ds_read_b64_tr_b16 v[176:177], v190 offset:0xe00
	s_waitcnt lgkmcnt(6)
	v_mfma_f32_32x32x16_bf16 v[20:35], v[152:155], v[178:181], v[20:35]
	ds_read_b64_tr_b16 v[178:179], v190 offset:0x1600
	ds_read_b64_tr_b16 v[180:181], v190 offset:0x1e00
	s_waitcnt lgkmcnt(6)
	v_mfma_f32_32x32x16_bf16 v[20:35], v[156:159], v[182:185], v[20:35]
	ds_read_b64_tr_b16 v[182:183], v190 offset:0x2600
	ds_read_b64_tr_b16 v[184:185], v190 offset:0x2e00
	s_waitcnt lgkmcnt(6)
	v_mfma_f32_32x32x16_bf16 v[20:35], v[160:163], v[186:189], v[20:35]
	ds_read_b64_tr_b16 v[186:187], v190 offset:0x3600
	ds_read_b64_tr_b16 v[188:189], v190 offset:0x3e00
	s_waitcnt lgkmcnt(6)
	v_mfma_f32_32x32x16_bf16 v[4:19], v[148:151], v[174:177], v[4:19]
	s_andn2_b64 vcc, exec, s[36:37]
	s_waitcnt lgkmcnt(4)
	v_mfma_f32_32x32x16_bf16 v[4:19], v[152:155], v[178:181], v[4:19]
	s_waitcnt lgkmcnt(2)
	v_mfma_f32_32x32x16_bf16 v[4:19], v[156:159], v[182:185], v[4:19]
	s_waitcnt lgkmcnt(0)
	v_mfma_f32_32x32x16_bf16 v[4:19], v[160:163], v[186:189], v[4:19]
	s_cbranch_vccnz .LBB0_323
	s_lshl_b32 s5, s0, 14
	s_waitcnt vmcnt(0)
	s_add_i32 s5, s5, 0
	v_add_u32_e32 v148, s5, v214
	s_waitcnt vmcnt(1)
	ds_write_b128 v168, v[136:139]
	s_waitcnt vmcnt(0)
	ds_write_b128 v168, v[144:147] offset:8192
	ds_write_b128 v148, v[100:103]
	v_add_u32_e32 v148, s5, v215
	ds_write_b128 v148, v[104:107]
.LBB0_323:
	s_waitcnt lgkmcnt(0)
	s_barrier
	s_cmp_gt_u32 s3, s24
	s_cbranch_scc1 .LBB0_325
	s_waitcnt vmcnt(0)
	s_add_u32 s98, s20, 0x10000
	s_addc_u32 s99, s21, 0
	s_add_u32 s100, s20, 0x12000
	s_addc_u32 s101, s21, 0
	global_load_dwordx4 v[100:103], v196, s[98:99]
	global_load_dwordx4 v[104:107], v196, s[100:101]
	s_add_u32 s98, s18, 0x10000
	s_addc_u32 s99, s19, 0
	s_add_u32 s100, s18, 0x12000
	s_addc_u32 s101, s19, 0
	global_load_dwordx4 v[136:139], v196, s[98:99]
	global_load_dwordx4 v[144:147], v196, s[100:101]

; __device__ __forceinline__ void partialSM(f32x16& p0, f32x16& p1, float& m_reg, float& mn, float& alpha) {
;     float pmax = p0[0];
; #pragma unroll
;     for (int r = 1; r < 16; ++r) pmax = fmaxf(pmax, p0[r]);
; #pragma unroll
;     for (int r = 0; r < 16; ++r) pmax = fmaxf(pmax, p1[r]);
;     { auto rr = __builtin_amdgcn_permlane32_swap(__float_as_uint(pmax), __float_as_uint(pmax), false, false);
;       pmax = fmaxf(__uint_as_float(rr[0]), __uint_as_float(rr[1])); }
;     constexpr float C2 = 1.4426950408889634f * SCALE;
;     if (__builtin_expect(__all((pmax - m_reg) * SCALE <= THR), 1)) { mn = m_reg; alpha = 1.f; }
;     else { mn = fmaxf(m_reg, pmax); alpha = __builtin_amdgcn_exp2f((m_reg - mn) * C2); m_reg = mn; }
.LBB0_327:
	v_max_f32_e32 v148, v84, v85
	v_max3_f32 v148, v148, v86, v87
	v_max3_f32 v148, v148, v88, v89
	v_max3_f32 v148, v148, v90, v91
	v_max3_f32 v148, v148, v92, v93
	v_max3_f32 v148, v148, v94, v95
	v_max3_f32 v148, v148, v96, v97
	v_max3_f32 v148, v148, v98, v99
	v_max3_f32 v148, v148, v68, v69
	v_max3_f32 v148, v148, v70, v71
	v_max3_f32 v148, v148, v72, v73
	v_max3_f32 v148, v148, v74, v75
	v_max3_f32 v148, v148, v76, v77
	v_max3_f32 v148, v148, v78, v79
	v_max3_f32 v148, v148, v80, v81
	v_max3_f32 v148, v148, v82, v83
	v_mov_b32_e32 v149, v148
	s_nop 1
	v_permlane32_swap_b32_e32 v148, v149
	v_max_f32_e32 v148, v148, v149
	v_sub_f32_e32 v149, v148, v171
	v_mul_f32_e32 v149, 0x3db504f3, v149
	v_cmp_ge_f32_e32 vcc, s15, v149
	v_max_f32_e32 v149, v171, v148
	v_sub_f32_e32 v148, v171, v149
	v_mul_f32_e32 v148, 0x3e0293ee, v148
	v_exp_f32_e32 v148, v148
	s_cmp_eq_u64 vcc, exec
	s_cselect_b64 s[38:39], -1, 0
	v_cndmask_b32_e64 v148, v148, 1.0, s[38:39]
	v_cmp_gt_f32_e32 vcc, 1.0, v148
	s_cbranch_vccz .LBB0_331
	s_and_saveexec_b64 s[36:37], s[16:17]
	ds_write_b32 v234, v148 offset:128
	s_or_b64 exec, exec, s[36:37]
	s_waitcnt lgkmcnt(0)
	ds_read_b128 v[150:153], v205 offset:224
	ds_read_b128 v[154:157], v205 offset:192
	ds_read_b128 v[158:161], v205 offset:160
	ds_read_b128 v[162:165], v205 offset:128
	s_waitcnt lgkmcnt(3)
	v_pk_mul_f32 v[66:67], v[66:67], v[152:153]
	s_waitcnt lgkmcnt(2)
	v_pk_mul_f32 v[62:63], v[62:63], v[156:157]
	s_waitcnt lgkmcnt(1)
	v_pk_mul_f32 v[58:59], v[58:59], v[160:161]
	s_waitcnt lgkmcnt(0)
	v_pk_mul_f32 v[54:55], v[54:55], v[164:165]
	v_pk_mul_f32 v[64:65], v[64:65], v[150:151]
	v_pk_mul_f32 v[60:61], v[60:61], v[154:155]
	v_pk_mul_f32 v[56:57], v[56:57], v[158:159]
	v_pk_mul_f32 v[52:53], v[52:53], v[162:163]
	v_pk_mul_f32 v[50:51], v[50:51], v[152:153]
	v_pk_mul_f32 v[46:47], v[46:47], v[156:157]
	v_pk_mul_f32 v[42:43], v[42:43], v[160:161]
	v_pk_mul_f32 v[38:39], v[38:39], v[164:165]
	v_pk_mul_f32 v[48:49], v[48:49], v[150:151]
	v_pk_mul_f32 v[44:45], v[44:45], v[154:155]
	v_pk_mul_f32 v[40:41], v[40:41], v[158:159]
	v_pk_mul_f32 v[36:37], v[36:37], v[162:163]
	v_pk_mul_f32 v[34:35], v[34:35], v[152:153]
	v_pk_mul_f32 v[30:31], v[30:31], v[156:157]
	v_pk_mul_f32 v[26:27], v[26:27], v[160:161]
	v_pk_mul_f32 v[22:23], v[22:23], v[164:165]
	v_pk_mul_f32 v[32:33], v[32:33], v[150:151]
	v_pk_mul_f32 v[28:29], v[28:29], v[154:155]
	v_pk_mul_f32 v[24:25], v[24:25], v[158:159]
	v_pk_mul_f32 v[20:21], v[20:21], v[162:163]
	v_pk_mul_f32 v[18:19], v[18:19], v[152:153]
	v_pk_mul_f32 v[14:15], v[14:15], v[156:157]
	v_pk_mul_f32 v[10:11], v[10:11], v[160:161]
	v_pk_mul_f32 v[6:7], v[6:7], v[164:165]
	v_pk_mul_f32 v[16:17], v[16:17], v[150:151]
	v_pk_mul_f32 v[12:13], v[12:13], v[154:155]
	v_pk_mul_f32 v[8:9], v[8:9], v[158:159]
	v_pk_mul_f32 v[4:5], v[4:5], v[162:163]
